# LayerNorm wave reductions: row sums combined via v_readlane + scalar-operand adds instead of two dependent ds_bpermute round trips
# baseline (speedup 1.0000x reference)
.LBB0_1225:
	v_mov_b32_e32 v112, v109
	v_mov_b32_e32 v113, v110
	v_mov_b32_e32 v109, v111
	v_mov_b32_e32 v110, v105
	v_mov_b32_e32 v111, v106
	v_mov_b32_e32 v105, v107
	v_pk_add_f32 v[120:121], v[112:113], v[108:109]
	v_mov_b32_e32 v116, v88
	v_add_f32_e32 v107, v120, v121
	v_pk_add_f32 v[120:121], v[110:111], v[104:105]
	v_mov_b32_e32 v118, v89
	v_pk_add_f32 v[120:121], v[120:121], v[120:121] op_sel_hi:[0,1]
	v_mov_b32_e32 v106, v90
	v_mov_b32_e32 v114, v91
	v_add_f32_e32 v115, 0, v107
	v_add_f32_e32 v117, v100, v101
	v_add_f32_e32 v119, v102, v103
	v_mov_b32_e32 v107, v121
	v_pk_add_f32 v[116:117], v[116:117], v[118:119]
	v_pk_add_f32 v[106:107], v[106:107], v[114:115]
	s_ashr_i32 s13, s12, 31
	v_pk_add_f32 v[106:107], v[116:117], v[106:107]
	s_nop 0
	v_add_f32_e32 v106, v106, v107
	s_nop 1
	v_add_f32_dpp v106, v106, v106 quad_perm:[1,0,3,2] row_mask:0xf bank_mask:0xf bound_ctrl:1
	s_nop 1
	v_add_f32_dpp v106, v106, v106 quad_perm:[2,3,0,1] row_mask:0xf bank_mask:0xf bound_ctrl:1
	s_nop 1
	v_add_f32_dpp v106, v106, v106 row_half_mirror row_mask:0xf bank_mask:0xf bound_ctrl:1
	s_nop 1
	v_add_f32_dpp v106, v106, v106 row_mirror row_mask:0xf bank_mask:0xf bound_ctrl:1
	s_waitcnt lgkmcnt(0)
	v_readlane_b32 s27, v106, 0
	v_readlane_b32 s28, v106, 16
	v_readlane_b32 s29, v106, 32
	v_readlane_b32 s32, v106, 48
	v_mov_b32_e32 v107, s27
	v_add_f32_e32 v107, s28, v107
	v_add_f32_e32 v107, s29, v107
	v_add_f32_e32 v107, s32, v107
	v_fmac_f32_e32 v109, 0xba800000, v107
	v_fmac_f32_e32 v113, 0xba800000, v107
	v_fmac_f32_e32 v112, 0xba800000, v107
	v_fmac_f32_e32 v108, 0xba800000, v107
	v_mov_b32_e32 v114, v113
	v_mov_b32_e32 v115, v109
	v_mov_b32_e32 v109, v112
	v_pk_mul_f32 v[116:117], v[114:115], v[114:115]
	v_pk_mul_f32 v[118:119], v[108:109], v[108:109]
	v_fmac_f32_e32 v105, 0xba800000, v107
	v_pk_mov_b32 v[120:121], v[118:119], v[116:117] op_sel:[1,0]
	v_mov_b32_e32 v119, v117
	v_fmac_f32_e32 v111, 0xba800000, v107
	v_fmac_f32_e32 v110, 0xba800000, v107
	v_fmac_f32_e32 v104, 0xba800000, v107
	v_pk_add_f32 v[116:117], v[120:121], v[118:119]
	v_mov_b32_e32 v118, v111
	v_mov_b32_e32 v119, v105
	v_mov_b32_e32 v120, v104
	v_mov_b32_e32 v121, v110
	v_pk_mul_f32 v[118:119], v[118:119], v[118:119]
	v_pk_mul_f32 v[120:121], v[120:121], v[120:121]
	v_fmac_f32_e32 v100, 0xba800000, v107
	v_pk_mov_b32 v[122:123], v[120:121], v[118:119] op_sel:[1,0]
	v_mov_b32_e32 v121, v119
	v_fmac_f32_e32 v102, 0xba800000, v107
	v_fmac_f32_e32 v101, 0xba800000, v107
	v_mul_f32_e32 v106, v100, v100
	v_pk_add_f32 v[118:119], v[122:123], v[120:121]
	v_fmac_f32_e32 v103, 0xba800000, v107
	v_pk_fma_f32 v[120:121], v[100:101], v[100:101], v[106:107] op_sel_hi:[1,1,0]
	v_mul_f32_e32 v106, v102, v102
	v_pk_add_f32 v[116:117], v[116:117], v[116:117] op_sel_hi:[0,1]
	v_pk_add_f32 v[118:119], v[118:119], v[118:119] op_sel_hi:[0,1]
	v_pk_fma_f32 v[122:123], v[102:103], v[102:103], v[106:107] op_sel_hi:[1,1,0]
	v_fmamk_f32 v91, v107, 0xba800000, v91
	v_fmamk_f32 v90, v107, 0xba800000, v90
	v_fmamk_f32 v89, v107, 0xba800000, v89
	v_fmac_f32_e32 v88, 0xba800000, v107
	v_mul_f32_e32 v120, v88, v88
	v_mul_f32_e32 v122, v89, v89
	v_mul_f32_e32 v116, v90, v90
	v_mul_f32_e32 v118, v91, v91
	v_pk_add_f32 v[120:121], v[120:121], v[122:123]
	v_pk_add_f32 v[116:117], v[116:117], v[118:119]
	s_nop 0
	v_pk_add_f32 v[116:117], v[120:121], v[116:117]
	s_nop 0
	v_add_f32_e32 v106, v116, v117
	s_nop 1
	v_add_f32_dpp v106, v106, v106 quad_perm:[1,0,3,2] row_mask:0xf bank_mask:0xf bound_ctrl:1
	s_nop 1
	v_add_f32_dpp v106, v106, v106 quad_perm:[2,3,0,1] row_mask:0xf bank_mask:0xf bound_ctrl:1
	s_nop 1
	v_add_f32_dpp v106, v106, v106 row_half_mirror row_mask:0xf bank_mask:0xf bound_ctrl:1
	s_nop 1
	v_add_f32_dpp v106, v106, v106 row_mirror row_mask:0xf bank_mask:0xf bound_ctrl:1
	s_waitcnt lgkmcnt(0)
	v_readlane_b32 s27, v106, 0
	v_readlane_b32 s28, v106, 16
	v_readlane_b32 s29, v106, 32
	v_readlane_b32 s32, v106, 48
	v_mov_b32_e32 v106, s27
	v_add_f32_e32 v106, s28, v106
	v_add_f32_e32 v106, s29, v106
	v_add_f32_e32 v106, s32, v106
	v_fmamk_f32 v106, v106, 0x3a800000, v204
	v_mul_f32_e32 v109, 0x4b800000, v106
	v_cmp_gt_f32_e32 vcc, s67, v106
	s_nop 1
	v_cndmask_b32_e32 v106, v106, v109, vcc
	v_rsq_f32_e32 v106, v106
	s_nop 0
	v_mul_f32_e32 v109, 0x45800000, v106
	v_cndmask_b32_e32 v106, v106, v109, vcc
	s_and_saveexec_b64 s[8:9], s[6:7]
	s_cbranch_execz .LBB0_1227
	s_lshl_b64 s[16:17], s[12:13], 3
	s_add_u32 s16, s23, s16
	v_mul_f32_e32 v116, 0x3a800000, v107
	s_addc_u32 s17, s24, s17
	v_mov_b32_e32 v117, v106
	global_store_dwordx2 v145, v[116:117], s[16:17]

.LBB0_1448:
	v_mov_b32_e32 v112, v101
	v_mov_b32_e32 v113, v102
	v_mov_b32_e32 v114, v100
	v_mov_b32_e32 v115, v103
	v_pk_add_f32 v[112:113], v[112:113], v[114:115]
	v_mov_b32_e32 v114, v105
	v_mov_b32_e32 v115, v106
	v_mov_b32_e32 v116, v104
	v_mov_b32_e32 v117, v107
	v_pk_add_f32 v[114:115], v[114:115], v[116:117]
	v_add_f32_e32 v112, v112, v113
	v_pk_add_f32 v[114:115], v[114:115], v[114:115] op_sel_hi:[0,1]
	v_add_f32_e32 v113, 0, v112
	v_add_f32_e32 v117, v108, v109
	v_add_f32_e32 v119, v110, v111
	v_mov_b32_e32 v116, v96
	v_mov_b32_e32 v118, v97
	v_mov_b32_e32 v114, v98
	v_mov_b32_e32 v112, v99
	v_pk_add_f32 v[116:117], v[116:117], v[118:119]
	v_pk_add_f32 v[112:113], v[114:115], v[112:113]
	s_nop 0
	v_pk_add_f32 v[112:113], v[116:117], v[112:113]
	s_nop 0
	v_add_f32_e32 v112, v112, v113
	s_nop 1
	v_add_f32_dpp v112, v112, v112 quad_perm:[1,0,3,2] row_mask:0xf bank_mask:0xf bound_ctrl:1
	s_nop 1
	v_add_f32_dpp v112, v112, v112 quad_perm:[2,3,0,1] row_mask:0xf bank_mask:0xf bound_ctrl:1
	s_nop 1
	v_add_f32_dpp v112, v112, v112 row_half_mirror row_mask:0xf bank_mask:0xf bound_ctrl:1
	s_nop 1
	v_add_f32_dpp v112, v112, v112 row_mirror row_mask:0xf bank_mask:0xf bound_ctrl:1
	s_waitcnt lgkmcnt(0)
	v_readlane_b32 s27, v112, 0
	v_readlane_b32 s28, v112, 16
	v_readlane_b32 s29, v112, 32
	v_readlane_b32 s32, v112, 48
	v_mov_b32_e32 v118, s27
	v_add_f32_e32 v118, s28, v118
	v_add_f32_e32 v118, s29, v118
	v_add_f32_e32 v118, s32, v118
	v_fmamk_f32 v115, v118, 0xba800000, v103
	v_fmamk_f32 v114, v118, 0xba800000, v102
	v_fmamk_f32 v117, v118, 0xba800000, v101
	v_fmamk_f32 v116, v118, 0xba800000, v100
	v_pk_mul_f32 v[100:101], v[114:115], v[114:115]
	v_pk_mul_f32 v[102:103], v[116:117], v[116:117]
	v_fmamk_f32 v107, v118, 0xba800000, v107
	v_pk_mov_b32 v[112:113], v[102:103], v[100:101] op_sel:[1,0]
	v_mov_b32_e32 v103, v101
	v_pk_add_f32 v[100:101], v[112:113], v[102:103]
	v_fmamk_f32 v106, v118, 0xba800000, v106
	v_fmamk_f32 v113, v118, 0xba800000, v105
	v_fmamk_f32 v112, v118, 0xba800000, v104
	v_pk_mul_f32 v[102:103], v[106:107], v[106:107]
	v_pk_mul_f32 v[104:105], v[112:113], v[112:113]
	v_pk_add_f32 v[100:101], v[100:101], v[100:101] op_sel_hi:[0,1]
	v_pk_mov_b32 v[126:127], v[104:105], v[102:103] op_sel:[1,0]
	v_mov_b32_e32 v105, v103
	v_pk_add_f32 v[102:103], v[126:127], v[104:105]
	v_fmamk_f32 v104, v118, 0xba800000, v108
	v_pk_add_f32 v[126:127], v[102:103], v[102:103] op_sel_hi:[0,1]
	v_fmamk_f32 v102, v118, 0xba800000, v110
	v_fmamk_f32 v105, v118, 0xba800000, v109
	v_mul_f32_e32 v100, v104, v104
	v_fmamk_f32 v103, v118, 0xba800000, v111
	v_pk_fma_f32 v[108:109], v[104:105], v[104:105], v[100:101] op_sel_hi:[1,1,0]
	v_mul_f32_e32 v100, v102, v102
	v_pk_fma_f32 v[110:111], v[102:103], v[102:103], v[100:101] op_sel_hi:[1,1,0]
	v_fmamk_f32 v99, v118, 0xba800000, v99
	v_fmamk_f32 v98, v118, 0xba800000, v98
	v_fmamk_f32 v97, v118, 0xba800000, v97
	v_fmac_f32_e32 v96, 0xba800000, v118
	v_mul_f32_e32 v108, v96, v96
	v_mul_f32_e32 v110, v97, v97
	v_mul_f32_e32 v100, v98, v98
	v_mul_f32_e32 v126, v99, v99
	v_pk_add_f32 v[108:109], v[108:109], v[110:111]
	v_pk_add_f32 v[100:101], v[100:101], v[126:127]
	s_nop 0
	v_pk_add_f32 v[100:101], v[108:109], v[100:101]
	s_nop 0
	v_add_f32_e32 v100, v100, v101
	s_nop 1
	v_add_f32_dpp v100, v100, v100 quad_perm:[1,0,3,2] row_mask:0xf bank_mask:0xf bound_ctrl:1
	s_nop 1
	v_add_f32_dpp v100, v100, v100 quad_perm:[2,3,0,1] row_mask:0xf bank_mask:0xf bound_ctrl:1
	s_nop 1
	v_add_f32_dpp v100, v100, v100 row_half_mirror row_mask:0xf bank_mask:0xf bound_ctrl:1
	s_nop 1
	v_add_f32_dpp v100, v100, v100 row_mirror row_mask:0xf bank_mask:0xf bound_ctrl:1
	s_waitcnt lgkmcnt(0)
	v_readlane_b32 s27, v100, 0
	v_readlane_b32 s28, v100, 16
	v_readlane_b32 s29, v100, 32
	v_readlane_b32 s32, v100, 48
	v_mov_b32_e32 v100, s27
	v_add_f32_e32 v100, s28, v100
	v_add_f32_e32 v100, s29, v100
	v_add_f32_e32 v100, s32, v100
	v_fmamk_f32 v100, v100, 0x3a800000, v204
	v_mul_f32_e32 v101, 0x4b800000, v100
	v_cmp_gt_f32_e32 vcc, s67, v100
	s_nop 1
	v_cndmask_b32_e32 v100, v100, v101, vcc
	v_rsq_f32_e32 v100, v100
	s_nop 0
	v_mul_f32_e32 v101, 0x45800000, v100
	v_cndmask_b32_e32 v100, v100, v101, vcc
	s_and_saveexec_b64 s[18:19], s[6:7]
	s_cbranch_execz .LBB0_1450
	s_lshl_b64 s[28:29], s[16:17], 3
	s_add_u32 s28, s25, s28
	v_mul_f32_e32 v108, 0x3a800000, v118
	s_addc_u32 s29, s26, s29
	v_mov_b32_e32 v109, v100
	global_store_dwordx2 v145, v[108:109], s[28:29]

.LBB0_1479:
	v_mov_b32_e32 v112, v101
	v_mov_b32_e32 v113, v102
	v_mov_b32_e32 v114, v100
	v_mov_b32_e32 v115, v103
	v_pk_add_f32 v[112:113], v[112:113], v[114:115]
	v_mov_b32_e32 v114, v105
	v_mov_b32_e32 v115, v106
	v_mov_b32_e32 v116, v104
	v_mov_b32_e32 v117, v107
	v_pk_add_f32 v[114:115], v[114:115], v[116:117]
	v_add_f32_e32 v112, v112, v113
	v_pk_add_f32 v[114:115], v[114:115], v[114:115] op_sel_hi:[0,1]
	v_add_f32_e32 v113, 0, v112
	v_add_f32_e32 v117, v108, v109
	v_add_f32_e32 v119, v110, v111
	v_mov_b32_e32 v116, v88
	v_mov_b32_e32 v118, v89
	v_mov_b32_e32 v114, v90
	v_mov_b32_e32 v112, v91
	v_pk_add_f32 v[116:117], v[116:117], v[118:119]
	v_pk_add_f32 v[112:113], v[114:115], v[112:113]
	s_ashr_i32 s15, s14, 31
	v_pk_add_f32 v[112:113], v[116:117], v[112:113]
	s_nop 0
	v_add_f32_e32 v112, v112, v113
	s_nop 1
	v_add_f32_dpp v112, v112, v112 quad_perm:[1,0,3,2] row_mask:0xf bank_mask:0xf bound_ctrl:1
	s_nop 1
	v_add_f32_dpp v112, v112, v112 quad_perm:[2,3,0,1] row_mask:0xf bank_mask:0xf bound_ctrl:1
	s_nop 1
	v_add_f32_dpp v112, v112, v112 row_half_mirror row_mask:0xf bank_mask:0xf bound_ctrl:1
	s_nop 1
	v_add_f32_dpp v112, v112, v112 row_mirror row_mask:0xf bank_mask:0xf bound_ctrl:1
	s_waitcnt lgkmcnt(0)
	v_readlane_b32 s27, v112, 0
	v_readlane_b32 s28, v112, 16
	v_readlane_b32 s29, v112, 32
	v_readlane_b32 s32, v112, 48
	v_mov_b32_e32 v118, s27
	v_add_f32_e32 v118, s28, v118
	v_add_f32_e32 v118, s29, v118
	v_add_f32_e32 v118, s32, v118
	v_fmamk_f32 v115, v118, 0xba800000, v103
	v_fmamk_f32 v114, v118, 0xba800000, v102
	v_fmamk_f32 v117, v118, 0xba800000, v101
	v_fmamk_f32 v116, v118, 0xba800000, v100
	v_pk_mul_f32 v[100:101], v[114:115], v[114:115]
	v_pk_mul_f32 v[102:103], v[116:117], v[116:117]
	v_fmamk_f32 v107, v118, 0xba800000, v107
	v_pk_mov_b32 v[112:113], v[102:103], v[100:101] op_sel:[1,0]
	v_mov_b32_e32 v103, v101
	v_pk_add_f32 v[100:101], v[112:113], v[102:103]
	v_fmamk_f32 v106, v118, 0xba800000, v106
	v_fmamk_f32 v113, v118, 0xba800000, v105
	v_fmamk_f32 v112, v118, 0xba800000, v104
	v_pk_mul_f32 v[102:103], v[106:107], v[106:107]
	v_pk_mul_f32 v[104:105], v[112:113], v[112:113]
	v_pk_add_f32 v[100:101], v[100:101], v[100:101] op_sel_hi:[0,1]
	v_pk_mov_b32 v[126:127], v[104:105], v[102:103] op_sel:[1,0]
	v_mov_b32_e32 v105, v103
	v_pk_add_f32 v[102:103], v[126:127], v[104:105]
	v_fmamk_f32 v104, v118, 0xba800000, v108
	v_pk_add_f32 v[126:127], v[102:103], v[102:103] op_sel_hi:[0,1]
	v_fmamk_f32 v102, v118, 0xba800000, v110
	v_fmamk_f32 v105, v118, 0xba800000, v109
	v_mul_f32_e32 v100, v104, v104
	v_fmamk_f32 v103, v118, 0xba800000, v111
	v_pk_fma_f32 v[108:109], v[104:105], v[104:105], v[100:101] op_sel_hi:[1,1,0]
	v_mul_f32_e32 v100, v102, v102
	v_pk_fma_f32 v[110:111], v[102:103], v[102:103], v[100:101] op_sel_hi:[1,1,0]
	v_fmamk_f32 v91, v118, 0xba800000, v91
	v_fmamk_f32 v90, v118, 0xba800000, v90
	v_fmamk_f32 v89, v118, 0xba800000, v89
	v_fmac_f32_e32 v88, 0xba800000, v118
	v_mul_f32_e32 v108, v88, v88
	v_mul_f32_e32 v110, v89, v89
	v_mul_f32_e32 v100, v90, v90
	v_mul_f32_e32 v126, v91, v91
	v_pk_add_f32 v[108:109], v[108:109], v[110:111]
	v_pk_add_f32 v[100:101], v[100:101], v[126:127]
	s_nop 0
	v_pk_add_f32 v[100:101], v[108:109], v[100:101]
	s_nop 0
	v_add_f32_e32 v100, v100, v101
	s_nop 1
	v_add_f32_dpp v100, v100, v100 quad_perm:[1,0,3,2] row_mask:0xf bank_mask:0xf bound_ctrl:1
	s_nop 1
	v_add_f32_dpp v100, v100, v100 quad_perm:[2,3,0,1] row_mask:0xf bank_mask:0xf bound_ctrl:1
	s_nop 1
	v_add_f32_dpp v100, v100, v100 row_half_mirror row_mask:0xf bank_mask:0xf bound_ctrl:1
	s_nop 1
	v_add_f32_dpp v100, v100, v100 row_mirror row_mask:0xf bank_mask:0xf bound_ctrl:1
	s_waitcnt lgkmcnt(0)
	v_readlane_b32 s27, v100, 0
	v_readlane_b32 s28, v100, 16
	v_readlane_b32 s29, v100, 32
	v_readlane_b32 s32, v100, 48
	v_mov_b32_e32 v100, s27
	v_add_f32_e32 v100, s28, v100
	v_add_f32_e32 v100, s29, v100
	v_add_f32_e32 v100, s32, v100
	v_fmamk_f32 v100, v100, 0x3a800000, v204
	v_mul_f32_e32 v101, 0x4b800000, v100
	v_cmp_gt_f32_e32 vcc, s67, v100
	s_nop 1
	v_cndmask_b32_e32 v100, v100, v101, vcc
	v_rsq_f32_e32 v100, v100
	s_nop 0
	v_mul_f32_e32 v101, 0x45800000, v100
	v_cndmask_b32_e32 v100, v100, v101, vcc
	s_and_saveexec_b64 s[8:9], s[6:7]
	s_cbranch_execz .LBB0_1481
	s_lshl_b64 s[18:19], s[14:15], 3
	s_add_u32 s18, s23, s18
	v_mul_f32_e32 v108, 0x3a800000, v118
	s_addc_u32 s19, s24, s19
	v_mov_b32_e32 v109, v100
	global_store_dwordx2 v145, v[108:109], s[18:19]
